# group seams signalled by per-member flag words written with plain stores (kept in the XCD's L2) and polled with one L1-bypassing 8/9-lane load, instead of memory-side atomic counters
# speedup vs baseline: 1.0004x; 1.0004x over previous
.LBB0_265:
	v_mov_b32_e32 v0, v147
	v_readlane_b32 s2, v255, 0
	s_mov_b32 s71, s39
	v_ashrrev_i32_e32 v1, 6, v0
	v_lshl_add_u32 v96, s2, 3, v1
	s_movk_i32 s2, 0x2000
	v_cmp_gt_i32_e32 vcc, s2, v96
	s_mul_i32 s2, s70, 0xc00
	v_writelane_b32 v255, s2, 12
	s_nop 1
	v_writelane_b32 v255, s3, 13
	s_and_saveexec_b64 s[16:17], vcc
	s_cbranch_execz .LBB0_280
	s_load_dwordx4 s[8:11], s[0:1], 0x90
	s_load_dwordx4 s[12:15], s[0:1], 0x0
	s_load_dwordx4 s[4:7], s[0:1], 0x40
	s_mul_i32 s2, s70, 0x2d000
	s_mul_i32 s24, s70, 0xc00
	s_waitcnt lgkmcnt(0)
	s_add_u32 s22, s10, 0x100000
	s_addc_u32 s23, s11, 0
	s_cmp_lg_u32 s70, 0
	s_cselect_b64 s[18:19], -1, 0
	s_add_u32 s20, s22, s2
	s_mul_hi_u32 s2, s70, 0x2d000
	s_addc_u32 s21, s23, s2
	s_mov_b32 s2, s24
	v_writelane_b32 v255, s2, 12
	v_sub_u32_e64 v1, s70, 1 clamp
	v_cmp_lt_i32_e32 vcc, v188, v183
	v_writelane_b32 v255, s3, 13
	s_movk_i32 s2, 0xc00
	v_mul_lo_u32 v144, v1, s2
	s_mov_b32 s2, 0x2d000
	v_lshlrev_b64 v[2:3], 2, v[144:145]
	v_mul_lo_u32 v144, v1, s2
	v_lshlrev_b32_e32 v1, 2, v0
	v_and_b32_e32 v98, 0xfc, v1
	v_cndmask_b32_e32 v1, v182, v188, vcc
	v_cmp_lt_i32_e32 vcc, v254, v183
	v_lshlrev_b32_e32 v99, 2, v1
	v_lshl_add_u64 v[4:5], s[22:23], 0, v[144:145]
	v_cndmask_b32_e32 v1, v182, v254, vcc
	v_lshlrev_b32_e32 v128, 2, v1
	v_xor_b32_e32 v1, 4, v182
	v_cmp_lt_i32_e32 vcc, v1, v183
	v_lshlrev_b32_e32 v144, 2, v98
	s_mov_b32 s25, s39
	v_cndmask_b32_e32 v1, v182, v1, vcc
	v_lshlrev_b32_e32 v129, 2, v1
	v_xor_b32_e32 v1, 8, v182
	v_lshl_add_u64 v[2:3], s[6:7], 0, v[2:3]
	v_lshl_add_u64 v[4:5], v[4:5], 0, v[144:145]
	s_mov_b64 s[6:7], 0x8000
	v_cmp_lt_i32_e32 vcc, v1, v183
	s_lshl_b64 s[24:25], s[24:25], 2
	v_lshl_add_u64 v[100:101], v[4:5], 0, s[6:7]
	v_lshl_add_u64 v[2:3], v[2:3], 0, v[144:145]
	s_mov_b64 s[6:7], 0x2000
	v_cndmask_b32_e32 v1, v182, v1, vcc
	v_cmp_lt_i32_e32 vcc, v187, v183
	v_ashrrev_i32_e32 v97, 31, v96
	s_add_u32 s4, s4, s24
	v_lshl_add_u64 v[102:103], v[2:3], 0, s[6:7]
	v_lshlrev_b32_e32 v130, 2, v1
	v_cndmask_b32_e32 v1, v182, v187, vcc
	v_cmp_lt_i32_e32 vcc, v184, v183
	v_lshlrev_b64 v[2:3], 11, v[96:97]
	v_and_b32_e32 v4, 63, v0
	s_addc_u32 s5, s5, s25
	v_lshlrev_b32_e32 v131, 2, v1
	v_cndmask_b32_e32 v1, v182, v184, vcc
	v_lshl_or_b32 v2, v4, 3, v2
	v_lshl_add_u64 v[104:105], s[4:5], 0, v[144:145]
	v_lshlrev_b32_e32 v132, 2, v1
	v_lshl_add_u64 v[0:1], s[10:11], 0, v[2:3]
	s_mov_b64 s[4:5], 0x9800600
	v_lshlrev_b64 v[108:109], 12, v[96:97]
	v_lshl_add_u64 v[106:107], v[0:1], 0, s[4:5]
	v_lshl_or_b32 v108, v4, 4, v108
	s_mov_b64 s[10:11], 0
	s_cmp_eq_u32 s70, 0
	s_cbranch_scc1 .Lnorm0_first
	v_readlane_b32 s2, v255, 0
	v_readfirstlane_b32 s7, v147
	s_load_dwordx2 s[4:5], s[0:1], 0x90
	s_load_dwordx2 s[12:13], s[0:1], 0x98
	s_load_dwordx2 s[14:15], s[0:1], 0x40
	s_load_dwordx2 s[40:41], s[0:1], 0x48
	v_and_b32_e32 v0, 63, v147
	v_lshlrev_b32_e32 v1, 3, v0
	v_lshlrev_b32_e32 v0, 4, v0
	s_lshr_b32 s7, s7, 6
	s_and_b32 s27, s2, 6
	s_lshl_b32 s27, s27, 5
	s_and_b32 s37, s2, 0x39
	s_or_b32 s27, s27, s37
	s_lshr_b32 s37, s2, 6
	s_lshl_b32 s37, s37, 1
	s_or_b32 s2, s27, s37
	s_lshl_b32 s2, s2, 3
	s_add_u32 s2, s2, s7
	s_lshl_b32 s24, s2, 2
	s_sub_u32 s27, s24, 0x1000
	s_lshr_b32 s27, s27, 10
	s_add_u32 s27, s27, 1
	s_cmp_lt_u32 s24, 0x1000
	s_cselect_b32 s30, 0, s27
	v_add_u32_e32 v2, 0x8000, v0
	v_mov_b32_e32 v3, v0
	v_add_u32_e32 v4, 0x1000, v0
	s_waitcnt lgkmcnt(0)
	s_lshl_b32 s27, s24, 11
	s_add_u32 s62, s12, s27
	s_addc_u32 s63, s13, 0
	s_add_u32 s58, s62, 0x8800000
	s_addc_u32 s59, s63, 0
	s_add_u32 s60, s58, 0x1000000
	s_addc_u32 s61, s59, 0
	s_add_u32 s62, s62, 0x1000000
	s_addc_u32 s63, s63, 0
	s_lshl_b32 s27, s24, 12
	s_add_u32 s46, s4, s27
	s_addc_u32 s47, s5, 0
	s_mov_b64 s[4:5], s[46:47]
	s_mul_i32 s27, s70, 5
	s_add_u32 s27, s27, s30
	s_mul_i32 s27, s27, 0x9000
	s_add_u32 s27, s27, 0x100000
	s_add_u32 s88, s12, s27
	s_addc_u32 s89, s13, 0
	s_sub_u32 s100, s88, 0x2d000
	s_subb_u32 s101, s89, 0
	s_mul_i32 s27, s70, 0x3000
	s_add_u32 s27, s27, 0xfffff000
	s_add_u32 s40, s40, s27
	s_addc_u32 s41, s41, 0
	s_mul_i32 s27, s70, 0x3000
	s_add_u32 s14, s14, s27
	s_addc_u32 s15, s15, 0
	global_load_dwordx4 v[22:25], v2, s[100:101] offset:0
	global_load_dwordx4 v[172:175], v0, s[40:41] offset:0
	global_load_dwordx4 v[38:41], v3, s[88:89] offset:0
	global_load_dwordx4 v[54:57], v4, s[88:89] offset:0
	global_load_dwordx4 v[234:237], v0, s[14:15] offset:0
	global_load_dwordx4 v[26:29], v2, s[100:101] offset:1024
	global_load_dwordx4 v[176:179], v0, s[40:41] offset:1024
	global_load_dwordx4 v[42:45], v3, s[88:89] offset:1024
	global_load_dwordx4 v[58:61], v4, s[88:89] offset:1024
	global_load_dwordx4 v[238:241], v0, s[14:15] offset:1024
	global_load_dwordx4 v[30:33], v2, s[100:101] offset:2048
	global_load_dwordx4 v[204:207], v0, s[40:41] offset:2048
	global_load_dwordx4 v[46:49], v3, s[88:89] offset:2048
	global_load_dwordx4 v[62:65], v4, s[88:89] offset:2048
	global_load_dwordx4 v[242:245], v0, s[14:15] offset:2048
	global_load_dwordx4 v[34:37], v2, s[100:101] offset:3072
	global_load_dwordx4 v[214:217], v0, s[40:41] offset:3072
	global_load_dwordx4 v[50:53], v3, s[88:89] offset:3072
	global_load_dwordx4 v[66:69], v4, s[88:89] offset:3072
	global_load_dwordx4 v[246:249], v0, s[14:15] offset:3072
	global_load_dwordx4 v[70:73], v0, s[4:5] offset:0
	global_load_dwordx4 v[74:77], v0, s[4:5] offset:1024
	global_load_dwordx4 v[78:81], v0, s[4:5] offset:2048
	global_load_dwordx4 v[82:85], v0, s[4:5] offset:3072
	s_add_u32 s4, s4, 0x1000
	s_addc_u32 s5, s5, 0
	global_load_dwordx4 v[102:105], v0, s[4:5] offset:0
	global_load_dwordx4 v[106:109], v0, s[4:5] offset:1024
	global_load_dwordx4 v[110:113], v0, s[4:5] offset:2048
	global_load_dwordx4 v[114:117], v0, s[4:5] offset:3072
	s_add_u32 s4, s4, 0x1000
	s_addc_u32 s5, s5, 0
	global_load_dwordx4 v[154:157], v0, s[4:5] offset:0
	global_load_dwordx4 v[158:161], v0, s[4:5] offset:1024
	global_load_dwordx4 v[162:165], v0, s[4:5] offset:2048
	global_load_dwordx4 v[168:171], v0, s[4:5] offset:3072
	s_add_u32 s4, s4, 0x1000
	s_addc_u32 s5, s5, 0
	global_load_dwordx4 v[218:221], v0, s[4:5] offset:0
	global_load_dwordx4 v[222:225], v0, s[4:5] offset:1024
	global_load_dwordx4 v[226:229], v0, s[4:5] offset:2048
	global_load_dwordx4 v[230:233], v0, s[4:5] offset:3072
	s_add_u32 s4, s4, 0x1000
	s_addc_u32 s5, s5, 0
	s_waitcnt vmcnt(16)
	v_pk_mul_f32 v[22:23], v[22:23], v[172:173]
	v_pk_mul_f32 v[24:25], v[24:25], v[174:175]
	v_pk_mul_f32 v[26:27], v[26:27], v[176:177]
	v_pk_mul_f32 v[28:29], v[28:29], v[178:179]
	v_pk_mul_f32 v[30:31], v[30:31], v[204:205]
	v_pk_mul_f32 v[32:33], v[32:33], v[206:207]
	v_pk_mul_f32 v[34:35], v[34:35], v[214:215]
	v_pk_mul_f32 v[36:37], v[36:37], v[216:217]
	v_pk_add_f32 v[54:55], v[54:55], 1.0 op_sel_hi:[1,0]
	v_pk_mul_f32 v[54:55], v[54:55], v[234:235]
	v_pk_add_f32 v[56:57], v[56:57], 1.0 op_sel_hi:[1,0]
	v_pk_mul_f32 v[56:57], v[56:57], v[236:237]
	v_pk_add_f32 v[58:59], v[58:59], 1.0 op_sel_hi:[1,0]
	v_pk_mul_f32 v[58:59], v[58:59], v[238:239]
	v_pk_add_f32 v[60:61], v[60:61], 1.0 op_sel_hi:[1,0]
	v_pk_mul_f32 v[60:61], v[60:61], v[240:241]
	v_pk_add_f32 v[62:63], v[62:63], 1.0 op_sel_hi:[1,0]
	v_pk_mul_f32 v[62:63], v[62:63], v[242:243]
	v_pk_add_f32 v[64:65], v[64:65], 1.0 op_sel_hi:[1,0]
	v_pk_mul_f32 v[64:65], v[64:65], v[244:245]
	v_pk_add_f32 v[66:67], v[66:67], 1.0 op_sel_hi:[1,0]
	v_pk_mul_f32 v[66:67], v[66:67], v[246:247]
	v_pk_add_f32 v[68:69], v[68:69], 1.0 op_sel_hi:[1,0]
	v_pk_mul_f32 v[68:69], v[68:69], v[248:249]
	v_cmp_eq_u32_e32 vcc, 0, v147
	s_and_saveexec_b64 s[40:41], vcc
	s_cbranch_execz .Lnw_skip_n0g
	v_readlane_b32 s2, v255, 0
	v_readlane_b32 s7, v255, 46
	s_nop 0
	s_lshr_b32 s24, s2, 3
	s_and_b32 s24, s24, 7
	s_and_b32 s27, s2, 6
	s_lshl_b32 s27, s27, 2
	s_or_b32 s27, s27, s24
	s_lshl_b32 s27, s27, 7
	s_add_u32 s27, s27, 0xa000
	s_mov_b32 s30, 0
	s_mov_b64 exec, 0xff
	v_mbcnt_lo_u32_b32 v14, -1, 0
	v_lshlrev_b32_e32 v14, 2, v14
	v_add_u32_e32 v14, s27, v14
	v_mov_b32_e32 v15, s7
.Lnw_poll_n0g:
	global_load_dword v16, v14, s[12:13] sc1
	s_waitcnt vmcnt(0)
	v_cmp_ge_u32_e32 vcc, v16, v15
	s_nop 1
	s_cmp_eq_u32 vcc_lo, 0xff
	s_cbranch_scc1 .Lnw_pdone_n0g
	s_sleep 1
	s_add_u32 s30, s30, 1
	s_cmp_lt_u32 s30, 0x20000
	s_cbranch_scc1 .Lnw_poll_n0g
.Lnw_pdone_n0g:
	s_mov_b64 exec, 1
	s_branch .Lnw_skip_n0g
	v_mov_b32_e32 v14, s27
	s_mov_b32 s30, 0

.Lxb_noinv_1:
	v_cmp_eq_u32_e32 vcc, 0, v0
	s_and_saveexec_b64 s[0:1], vcc
	s_cbranch_execz .LBB0_332
	s_load_dwordx2 s[12:13], s[8:9], 0x98
	v_readlane_b32 s14, v255, 0
	v_readlane_b32 s15, v255, 48
	s_nop 0
	s_lshr_b32 s24, s14, 3
	s_and_b32 s24, s24, 7
	s_and_b32 s27, s14, 6
	s_lshl_b32 s27, s27, 2
	s_or_b32 s27, s27, s24
	s_and_b32 s30, s14, 3
	s_lshl_b32 s30, s30, 3
	s_or_b32 s30, s30, s24
	s_lshl_b32 s27, s27, 7
	s_add_u32 s27, s27, 0xc000
	v_readlane_b32 s35, v255, 45
	s_nop 0
	s_lshl_b32 s35, s35, 4
	s_add_u32 s15, s15, 8
	v_writelane_b32 v255, s15, 48
	s_lshr_b32 s24, s14, 6
	s_lshl_b32 s24, s24, 1
	s_and_b32 s32, s14, 1
	s_or_b32 s24, s24, s32
	s_lshl_b32 s24, s24, 2
	s_add_u32 s24, s24, s27
	v_mov_b32_e32 v0, s24
	v_mov_b32_e32 v6, s15
	s_waitcnt lgkmcnt(0)
	global_store_dword v0, v6, s[12:13]
	v_writelane_b32 v255, s27, 50
	v_writelane_b32 v255, s15, 51
	s_mov_b32 s34, 0xd000
	v_writelane_b32 v255, s34, 52
	v_writelane_b32 v255, s35, 53
	v_writelane_b32 v255, s12, 54
	v_writelane_b32 v255, s13, 55

.LBB0_336:
	v_readlane_b32 s26, v255, 0
	s_waitcnt vmcnt(9)
	v_mov_b32_e32 v14, v147
	s_cmpk_lt_i32 s26, 0x2c0
	v_readfirstlane_b32 s7, v14
	s_cbranch_scc0 .LBB0_352
	v_lshlrev_b32_e32 v0, 4, v14
	v_add_u32_e32 v1, 0x2000, v0
	v_ashrrev_i32_e32 v2, 31, v1
	v_lshrrev_b32_e32 v2, 22, v2
	s_load_dwordx2 s[0:1], s[8:9], 0x98
	v_add_u32_e32 v2, v1, v2
	v_ashrrev_i32_e32 v8, 10, v2
	v_mul_i32_i24_e32 v2, 0x400, v8
	v_sub_u32_e32 v1, v1, v2
	s_mul_i32 s5, s70, 0x2800000
	v_lshrrev_b32_e32 v2, 4, v1
	s_waitcnt lgkmcnt(0)
	s_add_u32 s5, s0, s5
	v_bitop3_b32 v1, v2, v1, 32 bitop3:0x6c
	s_addc_u32 s6, s1, 0
	v_ashrrev_i32_e32 v2, 31, v1
	s_add_u32 s27, s0, 0x1000000
	v_lshrrev_b32_e32 v2, 26, v2
	s_mul_i32 s4, s2, 0xb00000
	s_addc_u32 s30, s1, 0
	v_add_u32_e32 v2, v1, v2
	v_lshlrev_b32_e32 v3, 3, v8
	s_add_u32 s4, s5, s4
	v_ashrrev_i32_e32 v9, 6, v2
	v_and_b32_e32 v3, -16, v3
	s_addc_u32 s5, s6, 0
	v_add_u32_e32 v3, v9, v3
	s_add_u32 s31, s4, 0xc800000
	v_and_b32_e32 v4, 3, v9
	s_mov_b32 s4, 0x1fffe0
	v_lshrrev_b32_e32 v5, 2, v3
	v_lshlrev_b32_e32 v6, 1, v3
	v_and_b32_e32 v2, 0xc0, v2
	v_and_or_b32 v4, v3, s4, v4
	v_and_b32_e32 v5, 4, v5
	v_and_b32_e32 v6, 24, v6
	v_sub_u32_e32 v1, v1, v2
	v_or3_b32 v4, v4, v5, v6
	v_lshlrev_b32_e32 v5, 5, v8
	v_ashrrev_i16_sdwa v1, v189, sext(v1) dst_sel:DWORD dst_unused:UNUSED_PAD src0_sel:DWORD src1_sel:BYTE_0
	v_and_b32_e32 v5, 32, v5
	v_bfe_i32 v10, v1, 0, 16
	v_add_lshl_u32 v1, v5, v10, 1
	v_lshl_add_u32 v128, v4, 11, v1
	v_lshl_add_u32 v130, v3, 11, v1
	v_bfe_i32 v1, v14, 27, 1
	v_lshrrev_b32_e32 v1, 22, v1
	v_add_u32_e32 v1, v0, v1
	v_and_b32_e32 v1, 0xfffffc00, v1
	v_sub_u32_e32 v0, v0, v1
	v_lshrrev_b32_e32 v1, 4, v0
	v_bitop3_b32 v1, v1, v0, 32 bitop3:0x6c
	v_ashrrev_i32_e32 v0, 31, v0
	v_lshrrev_b32_e32 v0, 26, v0
	v_add_u32_e32 v0, v1, v0
	v_ashrrev_i32_e32 v11, 6, v0
	v_ashrrev_i32_e32 v0, 31, v14
	v_lshrrev_b32_e32 v0, 26, v0
	v_add_u32_e32 v0, v14, v0
	v_ashrrev_i32_e32 v12, 6, v0
	v_lshlrev_b32_e32 v0, 3, v12
	v_and_b32_e32 v0, -16, v0
	s_addc_u32 s33, s5, 0
	v_add_u32_e32 v0, v11, v0
	v_and_b32_e32 v2, 3, v11
	s_ashr_i32 s37, s26, 31
	v_and_or_b32 v2, v0, s4, v2
	s_lshr_b32 s4, s37, 29
	s_add_i32 s4, s26, s4
	s_ashr_i32 s12, s7, 6
	s_ashr_i32 s5, s4, 3
	s_and_b32 s4, s4, -8
	s_ashr_i32 s13, s7, 8
	s_lshl_b32 s36, s12, 10
	s_sub_i32 s4, s26, s4
	s_cmp_lt_i32 s4, 0
	s_movk_i32 s6, 0x59
	s_cselect_b32 s6, s6, 0x58
	s_mul_i32 s4, s4, s6
	s_add_i32 s4, s4, s5
	s_mul_hi_i32 s5, s4, 0x2e8ba2e9
	s_lshr_b32 s6, s5, 31
	s_ashr_i32 s5, s5, 5
	s_add_i32 s5, s5, s6
	s_lshl_b32 s14, s5, 3
	s_mulk_i32 s5, 0xb0
	s_sub_i32 s4, s4, s5
	s_bfe_u32 s5, s4, 0x3001c
	s_add_i32 s5, s4, s5
	s_sext_i32_i16 s6, s5
	s_and_b32 s5, s5, 0xfff8
	s_sub_i32 s4, s4, s5
	s_sext_i32_i16 s4, s4
	s_add_i32 s5, s14, s4
	s_ashr_i32 s4, s5, 31
	s_lshr_b32 s4, s4, 27
	s_add_i32 s14, s5, s4
	s_ashr_i32 s4, s14, 5
	s_andn2_b32 s14, s14, 31
	s_sub_i32 s24, s5, s14
	s_ashr_i32 s5, s4, 31
	s_ashr_i32 s25, s24, 31
	s_lshr_b32 s6, s6, 3
	s_lshl_b64 s[4:5], s[4:5], 11
	s_lshl_b64 s[14:15], s[24:25], 19
	v_lshrrev_b32_e32 v3, 2, v0
	v_lshlrev_b32_e32 v4, 1, v0
	s_add_u32 s16, s27, s14
	v_and_b32_e32 v3, 4, v3
	v_and_b32_e32 v4, 24, v4
	s_addc_u32 s17, s30, s15
	s_bfe_i64 s[14:15], s[6:7], 0x100000
	v_or3_b32 v2, v2, v3, v4
	v_mul_i32_i24_e32 v4, 64, v11
	s_lshl_b64 s[14:15], s[14:15], 19
	v_sub_u32_e32 v1, v1, v4
	s_add_u32 s14, s31, s14
	v_lshlrev_b32_e32 v3, 5, v12
	v_ashrrev_i16_sdwa v1, v189, sext(v1) dst_sel:DWORD dst_unused:UNUSED_PAD src0_sel:DWORD src1_sel:BYTE_0
	s_addc_u32 s15, s33, s15
	v_and_b32_e32 v3, 32, v3
	s_waitcnt vmcnt(7)
	v_bfe_i32 v13, v1, 0, 16
	s_add_u32 s42, s14, s4
	v_add_lshl_u32 v1, v3, v13, 1
	s_addc_u32 s43, s15, s5
	s_add_i32 s38, s36, 0
	v_lshl_add_u32 v144, v2, 11, v1
	s_add_i32 m0, s38, 0x10000
	v_lshl_add_u32 v132, v0, 11, v1
	global_load_lds_dwordx4 v144, s[42:43]
	s_add_i32 m0, s38, 0x12000
	s_add_u32 s14, s42, 0x40000
	global_load_lds_dwordx4 v128, s[42:43]
	s_addc_u32 s15, s43, 0
	s_add_i32 m0, s38, 0x14000
	v_mov_b32_e32 v129, v145
	global_load_lds_dwordx4 v144, s[14:15]
	s_add_i32 m0, s38, 0x16000
	s_add_u32 s54, s16, s4
	s_addc_u32 s55, s17, s5
	s_add_i32 s40, s38, 0x2000
	global_load_lds_dwordx4 v128, s[14:15]
	v_cmp_eq_u32_e32 vcc, 0, v147
	s_and_saveexec_b64 s[100:101], vcc
	s_cbranch_execz .Lgw_skip_fi
	v_readlane_b32 s56, v255, 54
	v_readlane_b32 s57, v255, 55
	v_readlane_b32 s58, v255, 50
	v_readlane_b32 s59, v255, 51
	v_readlane_b32 s60, v255, 52
	v_readlane_b32 s61, v255, 53
	s_mov_b32 s62, 0
	s_mov_b64 exec, 0x1ff
	v_mbcnt_lo_u32_b32 v20, -1, 0
	v_lshlrev_b32_e32 v20, 2, v20
	v_add_u32_e32 v20, s58, v20
	v_mov_b32_e32 v21, s59
	v_writelane_b32 v20, s60, 8
	v_writelane_b32 v21, s61, 8
.Lgw_poll_fi:
	global_load_dword v22, v20, s[56:57] sc1
	s_waitcnt vmcnt(0)
	v_cmp_ge_u32_e32 vcc, v22, v21
	s_nop 1
	s_cmp_eq_u32 vcc_lo, 0x1ff
	s_cbranch_scc1 .Lgw_done_fi
	s_sleep 1
	s_add_u32 s62, s62, 1
	s_cmp_lt_u32 s62, 0x20000
	s_cbranch_scc1 .Lgw_poll_fi

.Lxb_noinv_2:
	v_cmp_eq_u32_e32 vcc, 0, v0
	s_and_saveexec_b64 s[0:1], vcc
	s_xor_b64 s[0:1], exec, s[0:1]
	s_cbranch_execz .LBB0_438
	s_load_dwordx2 s[12:13], s[8:9], 0x98
	v_readlane_b32 s14, v255, 0
	v_readlane_b32 s15, v255, 45
	s_nop 0
	s_lshr_b32 s24, s14, 3
	s_and_b32 s24, s24, 7
	s_and_b32 s27, s14, 6
	s_lshl_b32 s27, s27, 2
	s_or_b32 s27, s27, s24
	s_and_b32 s30, s14, 3
	s_lshl_b32 s30, s30, 3
	s_or_b32 s30, s30, s24
	s_lshl_b32 s27, s27, 1
	s_and_b32 s24, s14, 1
	s_or_b32 s27, s27, s24
	s_lshl_b32 s27, s27, 7
	s_add_u32 s27, s27, 0x8000
	s_lshl_b32 s30, s30, 1
	s_bfe_u32 s24, s14, 0x10002
	s_or_b32 s30, s30, s24
	s_lshl_b32 s30, s30, 7
	s_add_u32 s30, s30, 0x8000
	s_add_u32 s15, s15, 4
	v_writelane_b32 v255, s15, 45
	s_lshr_b32 s24, s14, 6
	s_lshl_b32 s24, s24, 2
	s_add_u32 s24, s24, s27
	v_mov_b32_e32 v0, s24
	v_mov_b32_e32 v6, s15
	s_waitcnt lgkmcnt(0)
	global_store_dword v0, v6, s[12:13]
	global_store_dword v0, v6, s[12:13] offset:16
	s_cmp_lt_u32 s14, 0xc0
	s_cbranch_scc1 .Lgs_nocw_b2
	v_mov_b32_e32 v10, 0xd000
	global_atomic_add v10, v189, s[12:13]

.LBB0_443:
	v_ashrrev_i32_e32 v1, 31, v8
	v_lshrrev_b32_e32 v1, 26, v1
	v_add_u32_e32 v1, v8, v1
	v_ashrrev_i32_e32 v9, 6, v1
	v_bfe_i32 v1, v8, 27, 1
	v_lshlrev_b32_e32 v0, 4, v8
	v_lshrrev_b32_e32 v1, 22, v1
	v_add_u32_e32 v1, v0, v1
	v_and_b32_e32 v1, 0xfffffc00, v1
	v_sub_u32_e32 v1, v0, v1
	s_mul_i32 s6, s2, 0x580000
	s_mul_i32 s2, s70, 0x2800000
	v_lshrrev_b32_e32 v2, 4, v1
	s_waitcnt lgkmcnt(0)
	s_add_u32 s9, s4, s2
	v_bitop3_b32 v2, v2, v1, 32 bitop3:0x6c
	v_ashrrev_i32_e32 v1, 31, v1
	s_addc_u32 s13, s5, 0
	v_lshrrev_b32_e32 v1, 26, v1
	s_add_u32 s2, s4, 0x5800000
	v_lshlrev_b32_e32 v3, 3, v9
	v_add_u32_e32 v1, v2, v1
	s_addc_u32 s30, s5, 0
	v_and_b32_e32 v3, -16, v3
	v_ashrrev_i32_e32 v11, 6, v1
	s_add_u32 s6, s9, s6
	v_add_u32_e32 v1, v11, v3
	v_lshlrev_b32_e32 v3, 5, v9
	s_addc_u32 s9, s13, 0
	v_and_b32_e32 v10, 32, v3
	v_mul_i32_i24_e32 v3, 64, v11
	s_add_u32 s31, s6, 0xde00000
	v_sub_u32_e32 v2, v2, v3
	s_addc_u32 s33, s9, 0
	v_ashrrev_i16_sdwa v2, v189, sext(v2) dst_sel:DWORD dst_unused:UNUSED_PAD src0_sel:DWORD src1_sel:BYTE_0
	v_lshlrev_b32_e32 v3, 1, v1
	v_lshrrev_b32_e32 v4, 2, v1
	v_and_b32_e32 v5, 3, v11
	s_mov_b32 s9, 0xffffe0
	v_bfe_i32 v12, v2, 0, 16
	v_and_b32_e32 v3, 24, v3
	v_and_b32_e32 v4, 4, v4
	v_and_or_b32 v5, v1, s9, v5
	s_movk_i32 s13, 0xb00
	v_add_u32_e32 v2, v10, v12
	v_or3_b32 v3, v5, v4, v3
	v_mul_lo_u32 v1, v1, s13
	v_add_lshl_u32 v128, v2, v1, 1
	v_mul_u32_u24_e32 v1, 0xb00, v3
	v_add_u32_e32 v0, 0x2000, v0
	v_add_lshl_u32 v130, v1, v2, 1
	v_ashrrev_i32_e32 v1, 31, v0
	v_lshrrev_b32_e32 v1, 22, v1
	v_add_u32_e32 v1, v0, v1
	v_ashrrev_i32_e32 v13, 10, v1
	v_mul_i32_i24_e32 v1, 0x400, v13
	v_sub_u32_e32 v0, v0, v1
	v_lshrrev_b32_e32 v1, 4, v0
	v_bitop3_b32 v0, v1, v0, 32 bitop3:0x6c
	v_ashrrev_i32_e32 v2, 31, v0
	v_lshrrev_b32_e32 v2, 26, v2
	s_add_i32 s7, s8, s7
	v_lshlrev_b32_e32 v1, 3, v13
	v_add_u32_e32 v2, v0, v2
	s_ashr_i32 s8, s7, 31
	v_and_b32_e32 v1, -16, v1
	v_ashrrev_i32_e32 v15, 6, v2
	s_lshr_b32 s8, s8, 27
	v_add_u32_e32 v1, v15, v1
	v_and_b32_e32 v4, 3, v15
	s_add_i32 s8, s7, s8
	v_and_or_b32 v4, v1, s9, v4
	s_ashr_i32 s9, s8, 5
	s_and_b32 s8, s8, 0xffe0
	s_sub_i32 s8, s7, s8
	s_bfe_i32 s7, s8, 0x80000
	s_bfe_u32 s7, s7, 0x3000c
	s_add_i32 s14, s8, s7
	s_bfe_i32 s7, s14, 0x80000
	s_and_b32 s14, s14, 0xf8
	s_sub_i32 s8, s8, s14
	s_lshl_b32 s9, s9, 3
	s_sext_i32_i8 s8, s8
	s_add_i32 s8, s9, s8
	s_ashr_i32 s9, s8, 31
	s_lshr_b32 s9, s9, 27
	s_add_i32 s9, s8, s9
	s_ashr_i32 s16, s9, 5
	s_andn2_b32 s9, s9, 31
	v_lshlrev_b32_e32 v3, 5, v13
	v_and_b32_e32 v2, 0xc0, v2
	s_sext_i32_i16 s15, s7
	s_sub_i32 s54, s8, s9
	v_and_b32_e32 v14, 32, v3
	v_sub_u32_e32 v0, v0, v2
	v_lshlrev_b32_e32 v2, 1, v1
	v_lshrrev_b32_e32 v3, 2, v1
	v_mul_lo_u32 v1, v1, s13
	s_ashr_i32 s13, s12, 6
	s_lshr_b32 s7, s15, 3
	s_mul_i32 s8, s54, 0x160000
	s_ashr_i32 s15, s15, 3
	s_ashr_i32 s6, s12, 8
	s_lshl_b32 s36, s13, 10
	s_ashr_i32 s9, s8, 31
	s_mul_hi_i32 s18, s15, 0x160000
	s_mul_i32 s15, s15, 0x160000
	s_add_u32 s15, s31, s15
	s_mul_i32 s17, s16, 0xb00
	s_addc_u32 s18, s33, s18
	s_mul_hi_i32 s14, s16, 0xb00
	s_add_u32 s20, s15, s17
	s_addc_u32 s21, s18, s14
	s_add_i32 s37, s36, 0
	v_ashrrev_i16_sdwa v0, v189, sext(v0) dst_sel:DWORD dst_unused:UNUSED_PAD src0_sel:DWORD src1_sel:BYTE_0
	s_add_i32 m0, s37, 0x10000
	v_bfe_i32 v16, v0, 0, 16
	v_and_b32_e32 v2, 24, v2
	v_and_b32_e32 v3, 4, v3
	global_load_lds_dwordx4 v130, s[20:21]
	s_add_i32 m0, s37, 0x12000
	v_add_u32_e32 v0, v14, v16
	v_or3_b32 v2, v4, v3, v2
	s_add_u32 s15, s2, s8
	v_add_lshl_u32 v132, v0, v1, 1
	v_mul_u32_u24_e32 v1, 0xb00, v2
	s_addc_u32 s19, s30, s9
	v_add_lshl_u32 v134, v1, v0, 1
	s_add_u32 s8, s20, 0xb0000
	global_load_lds_dwordx4 v134, s[20:21]
	s_addc_u32 s9, s21, 0
	s_add_i32 m0, s37, 0x14000
	v_mov_b32_e32 v131, v145
	global_load_lds_dwordx4 v130, s[8:9]
	s_add_i32 m0, s37, 0x16000
	s_add_u32 s18, s15, s17
	s_addc_u32 s19, s19, s14
	s_add_i32 s40, s37, 0x2000
	global_load_lds_dwordx4 v134, s[8:9]
	v_cmp_eq_u32_e32 vcc, 0, v147
	s_and_saveexec_b64 s[100:101], vcc
	s_cbranch_execz .Lgw_skip_fo
	v_readlane_b32 s56, v255, 54
	v_readlane_b32 s57, v255, 55
	v_readlane_b32 s58, v255, 50
	v_readlane_b32 s59, v255, 51
	v_readlane_b32 s60, v255, 52
	v_readlane_b32 s61, v255, 53
	s_mov_b32 s62, 0
	s_mov_b64 exec, 0x1ff
	v_mbcnt_lo_u32_b32 v20, -1, 0
	v_lshlrev_b32_e32 v20, 2, v20
	v_add_u32_e32 v20, s58, v20
	v_mov_b32_e32 v21, s59
	v_writelane_b32 v20, s60, 8
	v_writelane_b32 v21, s61, 8

.Lxb_noinv_3:
	v_cmp_eq_u32_e32 vcc, 0, v0
	s_and_saveexec_b64 s[4:5], vcc
	s_xor_b64 s[4:5], exec, s[4:5]
	s_cbranch_execz .LBB0_519
	s_load_dwordx2 s[12:13], s[0:1], 0x98
	v_readlane_b32 s14, v255, 0
	v_readlane_b32 s15, v255, 46
	s_nop 0
	s_lshr_b32 s24, s14, 3
	s_and_b32 s24, s24, 7
	s_and_b32 s27, s14, 6
	s_lshl_b32 s27, s27, 2
	s_or_b32 s27, s27, s24
	s_and_b32 s30, s14, 3
	s_lshl_b32 s30, s30, 3
	s_or_b32 s30, s30, s24
	s_lshl_b32 s27, s27, 7
	s_add_u32 s27, s27, 0xa000
	s_lshl_b32 s30, s30, 7
	s_add_u32 s30, s30, 0xa000
	s_add_u32 s15, s15, 8
	v_writelane_b32 v255, s15, 46
	s_lshr_b32 s24, s14, 6
	s_bfe_u32 s32, s14, 0x10002
	s_lshl_b32 s32, s32, 2
	s_or_b32 s24, s24, s32
	s_lshl_b32 s24, s24, 2
	s_add_u32 s24, s24, s30
	v_mov_b32_e32 v0, s24
	v_mov_b32_e32 v6, s15
	s_waitcnt lgkmcnt(0)
	global_store_dword v0, v6, s[12:13]
.LBB0_519:
	s_or_b64 exec, exec, s[4:5]
	s_mov_b64 s[4:5], -1
	v_writelane_b32 v255, s4, 19
	s_and_b64 vcc, exec, s[10:11]
	s_waitcnt lgkmcnt(0)
	v_writelane_b32 v255, s5, 20
	s_mov_b64 s[4:5], -1
	s_barrier
	s_cbranch_vccz .LBB0_335
	s_mov_b64 s[16:17], s[0:1]
	v_mov_b32_e32 v0, v147
	v_readlane_b32 s2, v255, 0
	s_nop 0
	v_ashrrev_i32_e32 v1, 6, v0
	v_lshl_add_u32 v16, s2, 3, v1
	s_movk_i32 s2, 0x2000
	v_cmp_gt_i32_e32 vcc, s2, v16
	s_and_saveexec_b64 s[8:9], vcc
	s_cbranch_execz .LBB0_523
	s_load_dwordx4 s[4:7], s[16:17], 0x90
	s_load_dwordx4 s[12:15], s[16:17], 0x40
	v_lshlrev_b32_e32 v1, 2, v0
	v_cmp_lt_i32_e32 vcc, v188, v183
	v_and_b32_e32 v2, 0xfc, v1
	s_mul_i32 s2, s70, 0x2d000
	v_cndmask_b32_e32 v1, v182, v188, vcc
	v_cmp_lt_i32_e32 vcc, v254, v183
	s_waitcnt lgkmcnt(0)
	s_add_u32 s18, s6, s2
	s_mul_hi_u32 s2, s70, 0x2d000
	v_lshlrev_b32_e32 v28, 2, v1
	v_cndmask_b32_e32 v1, v182, v254, vcc
	s_addc_u32 s19, s7, s2
	v_readlane_b32 s20, v255, 12
	v_lshlrev_b32_e32 v29, 2, v1
	v_xor_b32_e32 v1, 4, v182
	s_add_u32 s10, s18, 0x103000
	v_readlane_b32 s21, v255, 13
	v_cmp_lt_i32_e32 vcc, v1, v183
	s_addc_u32 s11, s19, 0
	s_lshl_b64 s[20:21], s[20:21], 2
	v_cndmask_b32_e32 v1, v182, v1, vcc
	s_add_u32 s12, s12, s20
	v_lshlrev_b32_e32 v144, 2, v2
	v_lshlrev_b32_e32 v30, 2, v1
	v_xor_b32_e32 v1, 8, v182
	s_addc_u32 s13, s13, s21
	v_lshl_add_u64 v[4:5], s[18:19], 0, v[144:145]
	s_mov_b64 s[18:19], 0x102000
	v_cmp_lt_i32_e32 vcc, v1, v183
	v_lshl_add_u64 v[18:19], v[4:5], 0, s[18:19]
	v_lshl_add_u64 v[4:5], s[12:13], 0, v[144:145]
	v_cndmask_b32_e32 v1, v182, v1, vcc
	v_cmp_lt_i32_e32 vcc, v187, v183
	v_ashrrev_i32_e32 v17, 31, v16
	v_lshl_add_u64 v[22:23], v[4:5], 0, s[94:95]
	v_lshlrev_b32_e32 v31, 2, v1
	v_cndmask_b32_e32 v1, v182, v187, vcc
	v_cmp_lt_i32_e32 vcc, v184, v183
	v_lshlrev_b64 v[4:5], 11, v[16:17]
	v_and_b32_e32 v3, 63, v0
	v_lshlrev_b32_e32 v32, 2, v1
	v_cndmask_b32_e32 v1, v182, v184, vcc
	v_lshl_or_b32 v4, v3, 3, v4
	v_lshlrev_b32_e32 v33, 2, v1
	v_lshl_add_u64 v[0:1], s[6:7], 0, v[4:5]
	s_mov_b64 s[6:7], 0x9800600
	s_add_u32 s14, s14, s20
	v_lshl_add_u64 v[24:25], v[0:1], 0, s[6:7]
	v_lshlrev_b64 v[0:1], 12, v[16:17]
	s_addc_u32 s15, s15, s21
	v_lshl_or_b32 v0, v3, 4, v0
	v_lshl_add_u64 v[20:21], s[14:15], 0, v[144:145]
	v_lshl_add_u64 v[26:27], s[4:5], 0, v[0:1]
	s_mov_b64 s[4:5], 0
	v_lshlrev_b32_e32 v144, 2, v2
	v_readlane_b32 s2, v255, 0
	v_readfirstlane_b32 s7, v147
	s_load_dwordx2 s[4:5], s[16:17], 0x90
	s_load_dwordx2 s[12:13], s[16:17], 0x98
	s_load_dwordx2 s[14:15], s[16:17], 0x40
	s_load_dwordx2 s[40:41], s[16:17], 0x48
	v_and_b32_e32 v0, 63, v147
	v_lshlrev_b32_e32 v1, 3, v0
	v_lshlrev_b32_e32 v0, 4, v0
	s_lshr_b32 s7, s7, 6
	s_and_b32 s27, s2, 6
	s_lshl_b32 s27, s27, 5
	s_and_b32 s37, s2, 0x39
	s_or_b32 s27, s27, s37
	s_lshr_b32 s37, s2, 6
	s_lshl_b32 s37, s37, 1
	s_or_b32 s2, s27, s37
	s_lshl_b32 s2, s2, 3
	s_add_u32 s2, s2, s7
	s_lshl_b32 s24, s2, 2
	s_sub_u32 s27, s24, 0x1000
	s_lshr_b32 s27, s27, 10
	s_add_u32 s27, s27, 1
	s_cmp_lt_u32 s24, 0x1000
	s_cselect_b32 s30, 0, s27
	v_add_u32_e32 v2, 0x2000, v0
	v_add_u32_e32 v3, 0x3000, v0
	v_add_u32_e32 v4, 0x4000, v0
	s_waitcnt lgkmcnt(0)
	s_lshl_b32 s27, s24, 11
	s_add_u32 s62, s12, s27
	s_addc_u32 s63, s13, 0
	s_add_u32 s58, s62, 0x8800000
	s_addc_u32 s59, s63, 0
	s_add_u32 s60, s58, 0x1000000
	s_addc_u32 s61, s59, 0
	s_add_u32 s62, s62, 0x1000000
	s_addc_u32 s63, s63, 0
	s_lshl_b32 s27, s24, 12
	s_add_u32 s46, s4, s27
	s_addc_u32 s47, s5, 0
	s_mov_b64 s[4:5], s[46:47]
	s_mul_i32 s27, s70, 5
	s_add_u32 s27, s27, s30
	s_mul_i32 s27, s27, 0x9000
	s_add_u32 s27, s27, 0x100000
	s_add_u32 s88, s12, s27
	s_addc_u32 s89, s13, 0
	s_mov_b64 s[100:101], s[88:89]
	s_mul_i32 s27, s70, 0x3000
	s_add_u32 s40, s40, s27
	s_addc_u32 s41, s41, 0
	s_mul_i32 s27, s70, 0x3000
	s_add_u32 s27, s27, 0x1000
	s_add_u32 s14, s14, s27
	s_addc_u32 s15, s15, 0
	global_load_dwordx4 v[22:25], v2, s[100:101] offset:0
	global_load_dwordx4 v[172:175], v0, s[40:41] offset:0
	global_load_dwordx4 v[38:41], v3, s[88:89] offset:0
	global_load_dwordx4 v[54:57], v4, s[88:89] offset:0
	global_load_dwordx4 v[234:237], v0, s[14:15] offset:0
	global_load_dwordx4 v[26:29], v2, s[100:101] offset:1024
	global_load_dwordx4 v[176:179], v0, s[40:41] offset:1024
	global_load_dwordx4 v[42:45], v3, s[88:89] offset:1024
	global_load_dwordx4 v[58:61], v4, s[88:89] offset:1024
	global_load_dwordx4 v[238:241], v0, s[14:15] offset:1024
	global_load_dwordx4 v[30:33], v2, s[100:101] offset:2048
	global_load_dwordx4 v[204:207], v0, s[40:41] offset:2048
	global_load_dwordx4 v[46:49], v3, s[88:89] offset:2048
	global_load_dwordx4 v[62:65], v4, s[88:89] offset:2048
	global_load_dwordx4 v[242:245], v0, s[14:15] offset:2048
	global_load_dwordx4 v[34:37], v2, s[100:101] offset:3072
	global_load_dwordx4 v[214:217], v0, s[40:41] offset:3072
	global_load_dwordx4 v[50:53], v3, s[88:89] offset:3072
	global_load_dwordx4 v[66:69], v4, s[88:89] offset:3072
	global_load_dwordx4 v[246:249], v0, s[14:15] offset:3072
	global_load_dwordx4 v[70:73], v0, s[4:5] offset:0
	global_load_dwordx4 v[74:77], v0, s[4:5] offset:1024
	global_load_dwordx4 v[78:81], v0, s[4:5] offset:2048
	global_load_dwordx4 v[82:85], v0, s[4:5] offset:3072
	s_add_u32 s4, s4, 0x1000
	s_addc_u32 s5, s5, 0
	global_load_dwordx4 v[102:105], v0, s[4:5] offset:0
	global_load_dwordx4 v[106:109], v0, s[4:5] offset:1024
	global_load_dwordx4 v[110:113], v0, s[4:5] offset:2048
	global_load_dwordx4 v[114:117], v0, s[4:5] offset:3072
	s_add_u32 s4, s4, 0x1000
	s_addc_u32 s5, s5, 0
	global_load_dwordx4 v[154:157], v0, s[4:5] offset:0
	global_load_dwordx4 v[158:161], v0, s[4:5] offset:1024
	global_load_dwordx4 v[162:165], v0, s[4:5] offset:2048
	global_load_dwordx4 v[168:171], v0, s[4:5] offset:3072
	s_add_u32 s4, s4, 0x1000
	s_addc_u32 s5, s5, 0
	global_load_dwordx4 v[218:221], v0, s[4:5] offset:0
	global_load_dwordx4 v[222:225], v0, s[4:5] offset:1024
	global_load_dwordx4 v[226:229], v0, s[4:5] offset:2048
	global_load_dwordx4 v[230:233], v0, s[4:5] offset:3072
	s_add_u32 s4, s4, 0x1000
	s_addc_u32 s5, s5, 0
	s_waitcnt vmcnt(16)
	v_pk_mul_f32 v[22:23], v[22:23], v[172:173]
	v_pk_mul_f32 v[24:25], v[24:25], v[174:175]
	v_pk_mul_f32 v[26:27], v[26:27], v[176:177]
	v_pk_mul_f32 v[28:29], v[28:29], v[178:179]
	v_pk_mul_f32 v[30:31], v[30:31], v[204:205]
	v_pk_mul_f32 v[32:33], v[32:33], v[206:207]
	v_pk_mul_f32 v[34:35], v[34:35], v[214:215]
	v_pk_mul_f32 v[36:37], v[36:37], v[216:217]
	v_pk_add_f32 v[54:55], v[54:55], 1.0 op_sel_hi:[1,0]
	v_pk_mul_f32 v[54:55], v[54:55], v[234:235]
	v_pk_add_f32 v[56:57], v[56:57], 1.0 op_sel_hi:[1,0]
	v_pk_mul_f32 v[56:57], v[56:57], v[236:237]
	v_pk_add_f32 v[58:59], v[58:59], 1.0 op_sel_hi:[1,0]
	v_pk_mul_f32 v[58:59], v[58:59], v[238:239]
	v_pk_add_f32 v[60:61], v[60:61], 1.0 op_sel_hi:[1,0]
	v_pk_mul_f32 v[60:61], v[60:61], v[240:241]
	v_pk_add_f32 v[62:63], v[62:63], 1.0 op_sel_hi:[1,0]
	v_pk_mul_f32 v[62:63], v[62:63], v[242:243]
	v_pk_add_f32 v[64:65], v[64:65], 1.0 op_sel_hi:[1,0]
	v_pk_mul_f32 v[64:65], v[64:65], v[244:245]
	v_pk_add_f32 v[66:67], v[66:67], 1.0 op_sel_hi:[1,0]
	v_pk_mul_f32 v[66:67], v[66:67], v[246:247]
	v_pk_add_f32 v[68:69], v[68:69], 1.0 op_sel_hi:[1,0]
	v_pk_mul_f32 v[68:69], v[68:69], v[248:249]
	v_cmp_eq_u32_e32 vcc, 0, v147
	s_and_saveexec_b64 s[40:41], vcc
	s_cbranch_execz .Lnw_skip_n1
	v_readlane_b32 s2, v255, 0
	v_readlane_b32 s7, v255, 46
	s_nop 0
	s_lshr_b32 s24, s2, 3
	s_and_b32 s24, s24, 7
	s_and_b32 s27, s2, 6
	s_lshl_b32 s27, s27, 2
	s_or_b32 s27, s27, s24
	s_lshl_b32 s27, s27, 7
	s_add_u32 s27, s27, 0xa000
	s_mov_b32 s30, 0
	s_mov_b64 exec, 0xff
	v_mbcnt_lo_u32_b32 v14, -1, 0
	v_lshlrev_b32_e32 v14, 2, v14
	v_add_u32_e32 v14, s27, v14
	v_mov_b32_e32 v15, s7

.Lxb_noinv_4:
	v_cmp_eq_u32_e32 vcc, 0, v0
	s_and_saveexec_b64 s[4:5], vcc
	s_cbranch_execz .LBB0_575
	s_load_dwordx2 s[12:13], s[16:17], 0x98
	v_readlane_b32 s14, v255, 0
	v_readlane_b32 s15, v255, 47
	s_nop 0
	s_lshr_b32 s24, s14, 3
	s_and_b32 s24, s24, 7
	s_and_b32 s27, s14, 6
	s_lshl_b32 s27, s27, 2
	s_or_b32 s27, s27, s24
	s_and_b32 s30, s14, 3
	s_lshl_b32 s30, s30, 3
	s_or_b32 s30, s30, s24
	s_lshl_b32 s27, s27, 7
	s_add_u32 s27, s27, 0xb000
	s_add_u32 s15, s15, 8
	v_writelane_b32 v255, s15, 47
	s_lshr_b32 s24, s14, 6
	s_lshl_b32 s24, s24, 1
	s_and_b32 s32, s14, 1
	s_or_b32 s24, s24, s32
	s_lshl_b32 s24, s24, 2
	s_add_u32 s24, s24, s27
	v_mov_b32_e32 v0, s24
	v_mov_b32_e32 v6, s15
	s_waitcnt lgkmcnt(0)
	global_store_dword v0, v6, s[12:13]
	v_writelane_b32 v255, s27, 50
	v_writelane_b32 v255, s15, 51
	v_writelane_b32 v255, s27, 52
	v_writelane_b32 v255, s15, 53
	v_writelane_b32 v255, s12, 54
	v_writelane_b32 v255, s13, 55

.LBB0_581:
	s_andn2_b64 vcc, exec, s[10:11]
	s_cbranch_vccnz .LBB0_921
	v_ashrrev_i32_e32 v1, 31, v10
	v_lshrrev_b32_e32 v1, 26, v1
	v_add_u32_e32 v1, v10, v1
	v_ashrrev_i32_e32 v8, 6, v1
	v_bfe_i32 v1, v10, 27, 1
	v_lshlrev_b32_e32 v0, 4, v10
	v_lshrrev_b32_e32 v1, 22, v1
	v_add_u32_e32 v1, v0, v1
	v_and_b32_e32 v1, 0xfffffc00, v1
	v_sub_u32_e32 v1, v0, v1
	v_lshrrev_b32_e32 v2, 4, v1
	v_bitop3_b32 v2, v2, v1, 32 bitop3:0x6c
	v_ashrrev_i32_e32 v1, 31, v1
	v_lshrrev_b32_e32 v1, 26, v1
	v_add_u32_e32 v1, v2, v1
	s_mul_i32 s7, s70, 0x2800000
	v_ashrrev_i32_e32 v9, 6, v1
	s_waitcnt lgkmcnt(0)
	s_add_u32 s7, s14, s7
	v_lshlrev_b32_e32 v3, 3, v8
	v_mul_i32_i24_e32 v4, 64, v9
	s_addc_u32 s9, s15, 0
	v_and_b32_e32 v3, -16, v3
	v_sub_u32_e32 v2, v2, v4
	s_add_u32 s51, s14, 0x1000000
	v_add_u32_e32 v1, v9, v3
	v_lshlrev_b32_e32 v3, 5, v8
	v_ashrrev_i16_sdwa v2, v189, sext(v2) dst_sel:DWORD dst_unused:UNUSED_PAD src0_sel:DWORD src1_sel:BYTE_0
	s_addc_u32 s71, s15, 0
	v_and_b32_e32 v3, 32, v3
	v_bfe_i32 v11, v2, 0, 16
	s_add_u32 s78, s7, 0xe900000
	v_and_b32_e32 v5, 3, v9
	s_mov_b32 s7, 0x1fffe0
	v_add_lshl_u32 v3, v3, v11, 1
	v_add_u32_e32 v0, 0x2000, v0
	v_lshlrev_b32_e32 v2, 1, v1
	v_lshrrev_b32_e32 v4, 2, v1
	v_and_or_b32 v5, v1, s7, v5
	v_lshl_add_u32 v132, v1, 11, v3
	v_ashrrev_i32_e32 v1, 31, v0
	v_lshrrev_b32_e32 v1, 22, v1
	v_add_u32_e32 v1, v0, v1
	v_ashrrev_i32_e32 v12, 10, v1
	v_mul_i32_i24_e32 v1, 0x400, v12
	v_sub_u32_e32 v0, v0, v1
	v_and_b32_e32 v2, 24, v2
	v_and_b32_e32 v4, 4, v4
	v_lshrrev_b32_e32 v1, 4, v0
	v_or3_b32 v2, v5, v4, v2
	v_bitop3_b32 v0, v1, v0, 32 bitop3:0x6c
	v_lshl_add_u32 v134, v2, 11, v3
	v_ashrrev_i32_e32 v2, 31, v0
	v_lshrrev_b32_e32 v2, 26, v2
	v_lshlrev_b32_e32 v1, 3, v12
	v_add_u32_e32 v2, v0, v2
	v_and_b32_e32 v1, -16, v1
	v_ashrrev_i32_e32 v13, 6, v2
	v_add_u32_e32 v1, v13, v1
	v_and_b32_e32 v4, 3, v13
	s_addc_u32 s79, s9, 0
	v_and_or_b32 v4, v1, s7, v4
	s_ashr_i32 s11, s2, 6
	s_ashr_i32 s7, s6, 31
	s_ashr_i32 s10, s2, 8
	s_lshl_b32 s86, s11, 10
	s_lshl_b64 s[18:19], s[6:7], 19
	s_add_u32 s7, s51, s18
	s_addc_u32 s20, s71, s19
	s_ashr_i32 s9, s8, 31
	s_lshl_b64 s[18:19], s[8:9], 19
	v_and_b32_e32 v2, 0xc0, v2
	s_add_u32 s9, s78, s18
	v_sub_u32_e32 v0, v0, v2
	s_addc_u32 s18, s79, s19
	v_ashrrev_i16_sdwa v0, v189, sext(v0) dst_sel:DWORD dst_unused:UNUSED_PAD src0_sel:DWORD src1_sel:BYTE_0
	s_add_u32 s42, s9, s4
	v_lshlrev_b32_e32 v3, 5, v12
	v_bfe_i32 v14, v0, 0, 16
	v_lshlrev_b32_e32 v0, 1, v1
	v_lshrrev_b32_e32 v2, 2, v1
	s_addc_u32 s43, s18, s5
	s_add_i32 s87, s86, 0
	v_and_b32_e32 v3, 32, v3
	v_and_b32_e32 v0, 24, v0
	v_and_b32_e32 v2, 4, v2
	s_add_i32 m0, s87, 0x10000
	v_or3_b32 v0, v4, v2, v0
	v_add_lshl_u32 v2, v3, v14, 1
	global_load_lds_dwordx4 v134, s[42:43]
	s_add_i32 m0, s87, 0x12000
	v_lshl_add_u32 v138, v0, 11, v2
	s_add_u32 s18, s42, 0x40000
	global_load_lds_dwordx4 v138, s[42:43]
	s_addc_u32 s19, s43, 0
	s_add_i32 m0, s87, 0x14000
	v_lshl_add_u32 v136, v1, 11, v2
	global_load_lds_dwordx4 v134, s[18:19]
	s_add_i32 m0, s87, 0x16000
	s_add_u32 s4, s7, s4
	s_addc_u32 s5, s20, s5
	s_add_i32 s76, s87, 0x2000
	global_load_lds_dwordx4 v138, s[18:19]
	v_cmp_eq_u32_e32 vcc, 0, v147
	s_and_saveexec_b64 s[100:101], vcc
	s_cbranch_execz .Lgw_skip_mi
	v_readlane_b32 s56, v255, 54
	v_readlane_b32 s57, v255, 55
	v_readlane_b32 s58, v255, 50
	v_readlane_b32 s59, v255, 51
	v_readlane_b32 s60, v255, 52
	v_readlane_b32 s61, v255, 53
	s_mov_b32 s62, 0
	s_mov_b64 exec, 0x1ff
	v_mbcnt_lo_u32_b32 v20, -1, 0
	v_lshlrev_b32_e32 v20, 2, v20
	v_add_u32_e32 v20, s58, v20
	v_mov_b32_e32 v21, s59
	v_writelane_b32 v20, s60, 8
	v_writelane_b32 v21, s61, 8

.LBB0_939:
	s_or_b64 exec, exec, s[12:13]
	v_cvt_f32_u32_e32 v4, v2
	s_waitcnt vmcnt(0)
	v_readfirstlane_b32 s2, v3
	v_sub_u32_e32 v3, 0, v2
	v_rcp_iflag_f32_e32 v4, v4
	v_add_u32_e32 v5, s2, v1
	v_mul_f32_e32 v4, 0x4f7ffffe, v4
	v_cvt_u32_f32_e32 v4, v4
	v_mul_lo_u32 v1, v3, v4
	v_mul_hi_u32 v1, v4, v1
	v_add_u32_e32 v1, v4, v1
	v_mul_hi_u32 v1, v5, v1
	v_mul_lo_u32 v3, v1, v2
	v_sub_u32_e32 v3, v5, v3
	v_add_u32_e32 v4, 1, v1
	v_cmp_ge_u32_e32 vcc, v3, v2
	s_nop 1
	v_cndmask_b32_e32 v1, v1, v4, vcc
	v_sub_u32_e32 v4, v3, v2
	v_cndmask_b32_e32 v3, v3, v4, vcc
	v_add_u32_e32 v4, 1, v1
	v_cmp_ge_u32_e32 vcc, v3, v2
	v_add_u32_e32 v3, 1, v5
	s_nop 0
	v_cndmask_b32_e32 v1, v1, v4, vcc
	v_mul_lo_u32 v4, v2, v1
	v_add_u32_e32 v2, v4, v2
	v_cmp_ne_u32_e32 vcc, v3, v2
	s_and_saveexec_b64 s[10:11], vcc
	s_xor_b64 s[10:11], exec, s[10:11]
	s_cbranch_execz .LBB0_953
	v_readlane_b32 s18, v255, 0
	s_nop 0
	s_cmp_lt_u32 s18, 0x80
	s_cbranch_scc0 .Lb5_std
	s_bitcmp0_b32 s18, 0
	s_cbranch_scc0 .Lb5_std
	s_bfe_u32 s19, s18, 0x30003
	s_bfe_u32 s18, s18, 0x20001
	s_lshl_b32 s18, s18, 3
	s_or_b32 s18, s18, s19
	s_lshl_b32 s18, s18, 7
	s_add_u32 s18, s18, 0xb000
	v_readlane_b32 s19, v255, 47
	s_mov_b32 s2, 0
	s_waitcnt lgkmcnt(0)
	s_mov_b64 exec, 0xff
	v_mbcnt_lo_u32_b32 v0, -1, 0
	v_lshlrev_b32_e32 v0, 2, v0
	v_add_u32_e32 v0, s18, v0
	v_mov_b32_e32 v6, s19
.Lb5_poll:
	global_load_dword v2, v0, s[6:7] sc1
	s_waitcnt vmcnt(0)
	v_cmp_ge_u32_e32 vcc, v2, v6
	s_nop 1
	s_cmp_eq_u32 vcc_lo, 0xff
	s_cbranch_scc1 .Lb5_pdone
	s_sleep 1
	s_add_u32 s2, s2, 1
	s_cmp_lt_u32 s2, 0x20000
	s_cbranch_scc1 .Lb5_poll

.Lxb_noinv_7:
	v_cmp_eq_u32_e32 vcc, 0, v0
	s_and_saveexec_b64 s[4:5], vcc
	s_xor_b64 s[4:5], exec, s[4:5]
	s_cbranch_execz .LBB0_1222
	s_load_dwordx2 s[12:13], s[8:9], 0x98
	v_readlane_b32 s14, v255, 0
	v_readlane_b32 s15, v255, 46
	s_nop 0
	s_lshr_b32 s24, s14, 3
	s_and_b32 s24, s24, 7
	s_and_b32 s27, s14, 6
	s_lshl_b32 s27, s27, 2
	s_or_b32 s27, s27, s24
	s_and_b32 s30, s14, 3
	s_lshl_b32 s30, s30, 3
	s_or_b32 s30, s30, s24
	s_lshl_b32 s27, s27, 7
	s_add_u32 s27, s27, 0xa000
	s_lshl_b32 s30, s30, 7
	s_add_u32 s30, s30, 0xa000
	s_add_u32 s15, s15, 8
	v_writelane_b32 v255, s15, 46
	s_lshr_b32 s24, s14, 6
	s_bfe_u32 s32, s14, 0x10002
	s_lshl_b32 s32, s32, 2
	s_or_b32 s24, s24, s32
	s_lshl_b32 s24, s24, 2
	s_add_u32 s24, s24, s30
	v_mov_b32_e32 v0, s24
	v_mov_b32_e32 v6, s15
	s_waitcnt lgkmcnt(0)
	global_store_dword v0, v6, s[12:13]
.LBB0_1222:
	s_or_b64 exec, exec, s[4:5]
	s_waitcnt lgkmcnt(0)
	v_mov_b32_e32 v0, v147
	v_readlane_b32 s2, v255, 0
	s_barrier
	s_nop 0
	v_ashrrev_i32_e32 v1, 6, v0
	v_lshl_add_u32 v16, s2, 3, v1
	s_movk_i32 s2, 0x2000
	v_cmp_gt_i32_e32 vcc, s2, v16
	s_and_saveexec_b64 s[10:11], vcc
	s_cbranch_execz .LBB0_1225
	s_load_dwordx4 s[4:7], s[8:9], 0x90
	s_load_dwordx4 s[16:19], s[8:9], 0x40
	s_mul_i32 s2, s70, 0x2d000
	v_lshlrev_b32_e32 v1, 2, v0
	v_readlane_b32 s20, v255, 12
	s_waitcnt lgkmcnt(0)
	s_add_u32 s14, s6, s2
	s_mul_hi_u32 s2, s70, 0x2d000
	s_addc_u32 s15, s7, s2
	v_cmp_lt_i32_e32 vcc, v188, v183
	v_and_b32_e32 v2, 0xfc, v1
	s_add_u32 s12, s14, 0x106000
	v_readlane_b32 s21, v255, 13
	v_cndmask_b32_e32 v1, v182, v188, vcc
	v_cmp_lt_i32_e32 vcc, v254, v183
	s_addc_u32 s13, s15, 0
	s_lshl_b64 s[20:21], s[20:21], 2
	v_lshlrev_b32_e32 v28, 2, v1
	v_cndmask_b32_e32 v1, v182, v254, vcc
	s_add_u32 s16, s16, s20
	v_lshlrev_b32_e32 v29, 2, v1
	v_xor_b32_e32 v1, 4, v182
	s_addc_u32 s17, s17, s21
	v_cmp_lt_i32_e32 vcc, v1, v183
	s_add_u32 s18, s18, s20
	v_lshlrev_b32_e32 v144, 2, v2
	v_cndmask_b32_e32 v1, v182, v1, vcc
	s_addc_u32 s19, s19, s21
	v_lshl_add_u64 v[4:5], s[14:15], 0, v[144:145]
	s_mov_b64 s[14:15], 0x105000
	v_lshlrev_b32_e32 v30, 2, v1
	v_xor_b32_e32 v1, 8, v182
	v_lshl_add_u64 v[18:19], v[4:5], 0, s[14:15]
	v_lshl_add_u64 v[4:5], s[18:19], 0, v[144:145]
	v_cmp_lt_i32_e32 vcc, v1, v183
	v_lshl_add_u64 v[20:21], v[4:5], 0, s[94:95]
	v_lshl_add_u64 v[4:5], s[16:17], 0, v[144:145]
	s_mov_b64 s[14:15], 0x2000
	v_cndmask_b32_e32 v1, v182, v1, vcc
	v_cmp_lt_i32_e32 vcc, v187, v183
	v_ashrrev_i32_e32 v17, 31, v16
	v_lshl_add_u64 v[22:23], v[4:5], 0, s[14:15]
	v_lshlrev_b32_e32 v31, 2, v1
	v_cndmask_b32_e32 v1, v182, v187, vcc
	v_cmp_lt_i32_e32 vcc, v184, v183
	v_lshlrev_b64 v[4:5], 11, v[16:17]
	v_and_b32_e32 v3, 63, v0
	v_lshlrev_b32_e32 v32, 2, v1
	v_cndmask_b32_e32 v1, v182, v184, vcc
	v_lshl_or_b32 v4, v3, 3, v4
	v_lshlrev_b32_e32 v33, 2, v1
	v_lshl_add_u64 v[0:1], s[6:7], 0, v[4:5]
	s_mov_b64 s[6:7], 0x9800600
	v_lshl_add_u64 v[24:25], v[0:1], 0, s[6:7]
	v_lshlrev_b64 v[0:1], 12, v[16:17]
	v_lshl_or_b32 v0, v3, 4, v0
	v_lshl_add_u64 v[26:27], s[4:5], 0, v[0:1]
	s_mov_b64 s[4:5], 0
	v_lshlrev_b32_e32 v144, 2, v2
	v_readlane_b32 s2, v255, 0
	v_readfirstlane_b32 s7, v147
	s_load_dwordx2 s[4:5], s[8:9], 0x90
	s_load_dwordx2 s[12:13], s[8:9], 0x98
	s_load_dwordx2 s[14:15], s[8:9], 0x40
	s_load_dwordx2 s[40:41], s[8:9], 0x48
	v_and_b32_e32 v0, 63, v147
	v_lshlrev_b32_e32 v1, 3, v0
	v_lshlrev_b32_e32 v0, 4, v0
	s_lshr_b32 s7, s7, 6
	s_and_b32 s27, s2, 6
	s_lshl_b32 s27, s27, 5
	s_and_b32 s37, s2, 0x39
	s_or_b32 s27, s27, s37
	s_lshr_b32 s37, s2, 6
	s_lshl_b32 s37, s37, 1
	s_or_b32 s2, s27, s37
	s_lshl_b32 s2, s2, 3
	s_add_u32 s2, s2, s7
	s_lshl_b32 s24, s2, 2
	s_sub_u32 s27, s24, 0x1000
	s_lshr_b32 s27, s27, 10
	s_add_u32 s27, s27, 1
	s_cmp_lt_u32 s24, 0x1000
	s_cselect_b32 s30, 0, s27
	v_add_u32_e32 v2, 0x5000, v0
	v_add_u32_e32 v3, 0x6000, v0
	v_add_u32_e32 v4, 0x7000, v0
	s_waitcnt lgkmcnt(0)
	s_lshl_b32 s27, s24, 11
	s_add_u32 s62, s12, s27
	s_addc_u32 s63, s13, 0
	s_add_u32 s58, s62, 0x8800000
	s_addc_u32 s59, s63, 0
	s_add_u32 s60, s58, 0x1000000
	s_addc_u32 s61, s59, 0
	s_add_u32 s62, s62, 0x1000000
	s_addc_u32 s63, s63, 0
	s_lshl_b32 s27, s24, 12
	s_add_u32 s46, s4, s27
	s_addc_u32 s47, s5, 0
	s_mov_b64 s[4:5], s[46:47]
	s_mul_i32 s27, s70, 5
	s_add_u32 s27, s27, s30
	s_mul_i32 s27, s27, 0x9000
	s_add_u32 s27, s27, 0x100000
	s_add_u32 s88, s12, s27
	s_addc_u32 s89, s13, 0
	s_mov_b64 s[100:101], s[88:89]
	s_mul_i32 s27, s70, 0x3000
	s_add_u32 s27, s27, 0x1000
	s_add_u32 s40, s40, s27
	s_addc_u32 s41, s41, 0
	s_mul_i32 s27, s70, 0x3000
	s_add_u32 s27, s27, 0x2000
	s_add_u32 s14, s14, s27
	s_addc_u32 s15, s15, 0
	global_load_dwordx4 v[22:25], v2, s[100:101] offset:0
	global_load_dwordx4 v[172:175], v0, s[40:41] offset:0
	global_load_dwordx4 v[38:41], v3, s[88:89] offset:0
	global_load_dwordx4 v[54:57], v4, s[88:89] offset:0
	global_load_dwordx4 v[234:237], v0, s[14:15] offset:0
	global_load_dwordx4 v[26:29], v2, s[100:101] offset:1024
	global_load_dwordx4 v[176:179], v0, s[40:41] offset:1024
	global_load_dwordx4 v[42:45], v3, s[88:89] offset:1024
	global_load_dwordx4 v[58:61], v4, s[88:89] offset:1024
	global_load_dwordx4 v[238:241], v0, s[14:15] offset:1024
	global_load_dwordx4 v[30:33], v2, s[100:101] offset:2048
	global_load_dwordx4 v[204:207], v0, s[40:41] offset:2048
	global_load_dwordx4 v[46:49], v3, s[88:89] offset:2048
	global_load_dwordx4 v[62:65], v4, s[88:89] offset:2048
	global_load_dwordx4 v[242:245], v0, s[14:15] offset:2048
	global_load_dwordx4 v[34:37], v2, s[100:101] offset:3072
	global_load_dwordx4 v[214:217], v0, s[40:41] offset:3072
	global_load_dwordx4 v[50:53], v3, s[88:89] offset:3072
	global_load_dwordx4 v[66:69], v4, s[88:89] offset:3072
	global_load_dwordx4 v[246:249], v0, s[14:15] offset:3072
	global_load_dwordx4 v[70:73], v0, s[4:5] offset:0
	global_load_dwordx4 v[74:77], v0, s[4:5] offset:1024
	global_load_dwordx4 v[78:81], v0, s[4:5] offset:2048
	global_load_dwordx4 v[82:85], v0, s[4:5] offset:3072
	s_add_u32 s4, s4, 0x1000
	s_addc_u32 s5, s5, 0
	global_load_dwordx4 v[102:105], v0, s[4:5] offset:0
	global_load_dwordx4 v[106:109], v0, s[4:5] offset:1024
	global_load_dwordx4 v[110:113], v0, s[4:5] offset:2048
	global_load_dwordx4 v[114:117], v0, s[4:5] offset:3072
	s_add_u32 s4, s4, 0x1000
	s_addc_u32 s5, s5, 0
	global_load_dwordx4 v[154:157], v0, s[4:5] offset:0
	global_load_dwordx4 v[158:161], v0, s[4:5] offset:1024
	global_load_dwordx4 v[162:165], v0, s[4:5] offset:2048
	global_load_dwordx4 v[168:171], v0, s[4:5] offset:3072
	s_add_u32 s4, s4, 0x1000
	s_addc_u32 s5, s5, 0
	global_load_dwordx4 v[218:221], v0, s[4:5] offset:0
	global_load_dwordx4 v[222:225], v0, s[4:5] offset:1024
	global_load_dwordx4 v[226:229], v0, s[4:5] offset:2048
	global_load_dwordx4 v[230:233], v0, s[4:5] offset:3072
	s_add_u32 s4, s4, 0x1000
	s_addc_u32 s5, s5, 0
	s_waitcnt vmcnt(16)
	v_pk_mul_f32 v[22:23], v[22:23], v[172:173]
	v_pk_mul_f32 v[24:25], v[24:25], v[174:175]
	v_pk_mul_f32 v[26:27], v[26:27], v[176:177]
	v_pk_mul_f32 v[28:29], v[28:29], v[178:179]
	v_pk_mul_f32 v[30:31], v[30:31], v[204:205]
	v_pk_mul_f32 v[32:33], v[32:33], v[206:207]
	v_pk_mul_f32 v[34:35], v[34:35], v[214:215]
	v_pk_mul_f32 v[36:37], v[36:37], v[216:217]
	v_pk_add_f32 v[54:55], v[54:55], 1.0 op_sel_hi:[1,0]
	v_pk_mul_f32 v[54:55], v[54:55], v[234:235]
	v_pk_add_f32 v[56:57], v[56:57], 1.0 op_sel_hi:[1,0]
	v_pk_mul_f32 v[56:57], v[56:57], v[236:237]
	v_pk_add_f32 v[58:59], v[58:59], 1.0 op_sel_hi:[1,0]
	v_pk_mul_f32 v[58:59], v[58:59], v[238:239]
	v_pk_add_f32 v[60:61], v[60:61], 1.0 op_sel_hi:[1,0]
	v_pk_mul_f32 v[60:61], v[60:61], v[240:241]
	v_pk_add_f32 v[62:63], v[62:63], 1.0 op_sel_hi:[1,0]
	v_pk_mul_f32 v[62:63], v[62:63], v[242:243]
	v_pk_add_f32 v[64:65], v[64:65], 1.0 op_sel_hi:[1,0]
	v_pk_mul_f32 v[64:65], v[64:65], v[244:245]
	v_pk_add_f32 v[66:67], v[66:67], 1.0 op_sel_hi:[1,0]
	v_pk_mul_f32 v[66:67], v[66:67], v[246:247]
	v_pk_add_f32 v[68:69], v[68:69], 1.0 op_sel_hi:[1,0]
	v_pk_mul_f32 v[68:69], v[68:69], v[248:249]
	v_cmp_eq_u32_e32 vcc, 0, v147
	s_and_saveexec_b64 s[40:41], vcc
	s_cbranch_execz .Lnw_skip_n2
	v_readlane_b32 s2, v255, 0
	v_readlane_b32 s7, v255, 46
	s_nop 0
	s_lshr_b32 s24, s2, 3
	s_and_b32 s24, s24, 7
	s_and_b32 s27, s2, 6
	s_lshl_b32 s27, s27, 2
	s_or_b32 s27, s27, s24
	s_lshl_b32 s27, s27, 7
	s_add_u32 s27, s27, 0xa000
	s_mov_b32 s30, 0
	s_mov_b64 exec, 0xff
	v_mbcnt_lo_u32_b32 v14, -1, 0
	v_lshlrev_b32_e32 v14, 2, v14
	v_add_u32_e32 v14, s27, v14
	v_mov_b32_e32 v15, s7

.Lxb_noinv_8:
	v_cmp_eq_u32_e32 vcc, 0, v0
	s_and_saveexec_b64 s[4:5], vcc
	s_cbranch_execz .Ltramp_334
	s_load_dwordx2 s[12:13], s[8:9], 0x98
	v_readlane_b32 s14, v255, 0
	v_readlane_b32 s15, v255, 47
	s_nop 0
	s_lshr_b32 s24, s14, 3
	s_and_b32 s24, s24, 7
	s_and_b32 s27, s14, 6
	s_lshl_b32 s27, s27, 2
	s_or_b32 s27, s27, s24
	s_and_b32 s30, s14, 3
	s_lshl_b32 s30, s30, 3
	s_or_b32 s30, s30, s24
	s_lshl_b32 s27, s27, 7
	s_add_u32 s27, s27, 0xb000
	s_add_u32 s15, s15, 8
	v_writelane_b32 v255, s15, 47
	s_lshr_b32 s24, s14, 6
	s_lshl_b32 s24, s24, 1
	s_and_b32 s32, s14, 1
	s_or_b32 s24, s24, s32
	s_lshl_b32 s24, s24, 2
	s_add_u32 s24, s24, s27
	v_mov_b32_e32 v0, s24
	v_mov_b32_e32 v6, s15
	s_waitcnt lgkmcnt(0)
	global_store_dword v0, v6, s[12:13]
	v_writelane_b32 v255, s27, 50
	v_writelane_b32 v255, s15, 51
	v_writelane_b32 v255, s27, 52
	v_writelane_b32 v255, s15, 53
	v_writelane_b32 v255, s12, 54
	v_writelane_b32 v255, s13, 55
	s_branch .LBB0_334
.LBB0_1276:
	v_readlane_b32 s2, v255, 0
	s_nop 0
	v_ashrrev_i32_e32 v0, 6, v147
	v_lshl_add_u32 v32, s2, 3, v0
	s_movk_i32 s2, 0x2000
	v_cmp_gt_i32_e32 vcc, s2, v32
	s_and_saveexec_b64 s[2:3], vcc
	s_cbranch_execz .LBB0_1279
	v_readlane_b32 s2, v255, 0
	v_readfirstlane_b32 s7, v147
	s_load_dwordx2 s[4:5], s[0:1], 0x90
	s_load_dwordx2 s[12:13], s[0:1], 0x98
	s_load_dwordx2 s[40:41], s[0:1], 0x48
	v_and_b32_e32 v0, 63, v147
	v_lshlrev_b32_e32 v1, 3, v0
	v_lshlrev_b32_e32 v0, 4, v0
	s_lshr_b32 s7, s7, 6
	s_and_b32 s27, s2, 6
	s_lshl_b32 s27, s27, 5
	s_and_b32 s37, s2, 0x39
	s_or_b32 s27, s27, s37
	s_lshr_b32 s37, s2, 6
	s_lshl_b32 s37, s37, 1
	s_or_b32 s2, s27, s37
	s_lshl_b32 s2, s2, 3
	s_add_u32 s2, s2, s7
	s_lshl_b32 s24, s2, 2
	s_sub_u32 s27, s24, 0x1000
	s_lshr_b32 s27, s27, 10
	s_add_u32 s27, s27, 1
	s_cmp_lt_u32 s24, 0x1000
	s_cselect_b32 s30, 0, s27
	v_add_u32_e32 v2, 0x8000, v0
	v_mov_b32_e32 v3, v0
	v_add_u32_e32 v4, 0x1000, v0
	s_waitcnt lgkmcnt(0)
	s_lshl_b32 s27, s24, 11
	s_add_u32 s62, s12, s27
	s_addc_u32 s63, s13, 0
	s_add_u32 s58, s62, 0x8800000
	s_addc_u32 s59, s63, 0
	s_add_u32 s60, s58, 0x1000000
	s_addc_u32 s61, s59, 0
	s_add_u32 s62, s62, 0x1000000
	s_addc_u32 s63, s63, 0
	s_lshl_b32 s27, s24, 12
	s_add_u32 s46, s4, s27
	s_addc_u32 s47, s5, 0
	s_mov_b64 s[4:5], s[46:47]
	s_add_u32 s27, s30, 15
	s_mul_i32 s27, s27, 0x9000
	s_add_u32 s27, s27, 0x100000
	s_add_u32 s88, s12, s27
	s_addc_u32 s89, s13, 0
	s_mov_b64 s[100:101], s[88:89]
	s_mov_b32 s27, 0xb000
	s_add_u32 s40, s40, s27
	s_addc_u32 s41, s41, 0
	global_load_dwordx4 v[22:25], v2, s[100:101] offset:0
	global_load_dwordx4 v[118:121], v0, s[40:41] offset:0
	global_load_dwordx4 v[26:29], v2, s[100:101] offset:1024
	global_load_dwordx4 v[122:125], v0, s[40:41] offset:1024
	global_load_dwordx4 v[30:33], v2, s[100:101] offset:2048
	global_load_dwordx4 v[134:137], v0, s[40:41] offset:2048
	global_load_dwordx4 v[34:37], v2, s[100:101] offset:3072
	global_load_dwordx4 v[138:141], v0, s[40:41] offset:3072
	global_load_dwordx4 v[38:41], v0, s[4:5] offset:0
	global_load_dwordx4 v[42:45], v0, s[4:5] offset:1024
	global_load_dwordx4 v[46:49], v0, s[4:5] offset:2048
	global_load_dwordx4 v[50:53], v0, s[4:5] offset:3072
	s_add_u32 s4, s4, 0x1000
	s_addc_u32 s5, s5, 0
	global_load_dwordx4 v[70:73], v0, s[4:5] offset:0
	global_load_dwordx4 v[74:77], v0, s[4:5] offset:1024
	global_load_dwordx4 v[78:81], v0, s[4:5] offset:2048
	global_load_dwordx4 v[82:85], v0, s[4:5] offset:3072
	s_add_u32 s4, s4, 0x1000
	s_addc_u32 s5, s5, 0
	global_load_dwordx4 v[102:105], v0, s[4:5] offset:0
	global_load_dwordx4 v[106:109], v0, s[4:5] offset:1024
	global_load_dwordx4 v[110:113], v0, s[4:5] offset:2048
	global_load_dwordx4 v[114:117], v0, s[4:5] offset:3072
	s_add_u32 s4, s4, 0x1000
	s_addc_u32 s5, s5, 0
	global_load_dwordx4 v[154:157], v0, s[4:5] offset:0
	global_load_dwordx4 v[158:161], v0, s[4:5] offset:1024
	global_load_dwordx4 v[162:165], v0, s[4:5] offset:2048
	global_load_dwordx4 v[168:171], v0, s[4:5] offset:3072
	s_add_u32 s4, s4, 0x1000
	s_addc_u32 s5, s5, 0
	s_waitcnt vmcnt(16)
	v_pk_mul_f32 v[22:23], v[22:23], v[118:119]
	v_pk_mul_f32 v[24:25], v[24:25], v[120:121]
	v_pk_mul_f32 v[26:27], v[26:27], v[122:123]
	v_pk_mul_f32 v[28:29], v[28:29], v[124:125]
	v_pk_mul_f32 v[30:31], v[30:31], v[134:135]
	v_pk_mul_f32 v[32:33], v[32:33], v[136:137]
	v_pk_mul_f32 v[34:35], v[34:35], v[138:139]
	v_pk_mul_f32 v[36:37], v[36:37], v[140:141]
	v_cmp_eq_u32_e32 vcc, 0, v147
	s_and_saveexec_b64 s[40:41], vcc
	s_cbranch_execz .Lnw_skip_n3
	v_readlane_b32 s2, v255, 0
	v_readlane_b32 s7, v255, 46
	s_nop 0
	s_lshr_b32 s24, s2, 3
	s_and_b32 s24, s24, 7
	s_and_b32 s27, s2, 6
	s_lshl_b32 s27, s27, 2
	s_or_b32 s27, s27, s24
	s_lshl_b32 s27, s27, 7
	s_add_u32 s27, s27, 0xa000
	s_mov_b32 s30, 0
	s_mov_b64 exec, 0xff
	v_mbcnt_lo_u32_b32 v14, -1, 0
	v_lshlrev_b32_e32 v14, 2, v14
	v_add_u32_e32 v14, s27, v14
	v_mov_b32_e32 v15, s7
